# prep row loop: removed redundant under/overflow selects around the expf expansions (v_ldexp already saturates to 0/inf)
# baseline (speedup 1.0000x reference)
; #define LAS __attribute__((address_space(3)))
; __device__ __forceinline__ void phase_prep(const Args& A, const Ctx& C0, int l) {
;     ...
;         for (int tt = 0; tt < 8; ++tt) {
;             const float aw = outw[tt * 512 + c], aa = outa[tt * 512 + c];
;             const int row = row0 + tt;
;             const LAS float* cu = raw + (tt + 1) * DSH; const LAS float* pv = raw + tt * DSH;
;             const float r = cu[c] + (pv[c] - cu[c]) * mu_r, k = cu[512 + c] + (pv[512 + c] - cu[512 + c]) * mu_k, v = cu[1024 + c] + (pv[1024 + c] - cu[1024 + c]) * mu_v;
;             const float lw = w0 + aw; const float z = -lw;
;             const float sp = fmaxf(z, 0.f) + logf(1.f + expf(-fabsf(z)));
;             const float wraw = -sp - 0.5f; const float decay = expf(-expf(wraw));
;             const float ai = 1.f / (1.f + expf(-(a0 + aa)));
;             const float kkr = k * kkc; const float ss = wave_sum_l(kkr * kkr, C.lane);
;             const float kk = kkr / fmaxf(sqrtf(ss), 1e-12f);
;             const float k2 = k * (1.f + (ai - 1.f) * kac); const float b = kk * ai;
;             const float rk = wave_sum_l(r * k2 * rkc, C.lane);
;             float* s = SCN + (size_t)row * 3072 + head * 384 + C.lane;
;             __builtin_nontemporal_store(kk, s); __builtin_nontemporal_store(b, s + 64); __builtin_nontemporal_store(decay, s + 128); __builtin_nontemporal_store(k2, s + 192); __builtin_nontemporal_store(r, s + 256); __builtin_nontemporal_store(v, s + 320);
;             if (C.lane == 0) RKB[row * 8 + head] = rk;
.LBB0_98:
	v_add_u32_e32 v87, s30, v133
	v_add_u32_e32 v82, 0x13b00, v87
	v_add_u32_e32 v86, s74, v133
	ds_read_b32 v90, v87 offset:64256
	ds_read_b32 v91, v82
	ds_read2st64_b32 v[82:83], v86 offset0:16 offset1:26
	ds_read2st64_b32 v[88:89], v86 offset1:8
	ds_read2st64_b32 v[84:85], v86 offset0:34 offset1:42
	s_waitcnt lgkmcnt(0)
	v_sub_f32_e32 v88, v88, v83
	s_waitcnt lgkmcnt(0)
	v_sub_f32_e32 v82, v82, v85
	v_sub_f32_e32 v89, v89, v84
	v_fmac_f32_e32 v85, v123, v82
	v_add_f32_e32 v82, v116, v90
	v_fma_f32 v84, v122, v89, v84
	v_mul_f32_e64 v89, |v82|, s20
	v_fma_f32 v90, |v82|, s20, -v89
	v_rndne_f32_e32 v92, v89
	v_fma_f32 v90, |v82|, s21, v90
	v_sub_f32_e32 v89, v89, v92
	v_add_f32_e32 v89, v89, v90
	v_exp_f32_e32 v89, v89
	v_cvt_i32_f32_e32 v90, v92
	v_fmac_f32_e32 v83, v121, v88
	v_max_f32_e64 v88, -v82, 0
	v_ldexp_f32 v89, v89, v90
	v_mov_b32_e32 v82, v89
	v_add_f32_e32 v82, 1.0, v82
	v_cmp_gt_f32_e32 vcc, s35, v82
	s_nop 1
	v_cndmask_b32_e64 v89, 0, 32, vcc
	v_ldexp_f32 v82, v82, v89
	v_log_f32_e32 v82, v82
	s_nop 0
	v_mul_f32_e32 v89, 0x3f317217, v82
	v_fma_f32 v89, v82, s4, -v89
	v_fmac_f32_e32 v89, 0x3377d1cf, v82
	v_fmac_f32_e32 v89, 0x3f317217, v82
	v_cmp_lt_f32_e64 s[0:1], |v82|, s34
	s_nop 1
	v_cndmask_b32_e64 v82, v82, v89, s[0:1]
	v_cndmask_b32_e32 v89, 0, v142, vcc
	v_sub_f32_e32 v82, v82, v89
	v_add_f32_e32 v82, v88, v82
	v_sub_f32_e32 v82, -0.5, v82
	v_mul_f32_e32 v88, 0x3fb8aa3b, v82
	v_fma_f32 v89, v82, s97, -v88
	v_rndne_f32_e32 v90, v88
	v_fmac_f32_e32 v89, 0x32a5705f, v82
	v_sub_f32_e32 v88, v88, v90
	v_add_f32_e32 v88, v88, v89
	v_exp_f32_e32 v88, v88
	v_cvt_i32_f32_e32 v89, v90
	v_ldexp_f32 v88, v88, v89
	v_mov_b32_e32 v82, v88
	v_mul_f32_e32 v88, 0xbfb8aa3b, v82
	v_fma_f32 v89, v82, s20, -v88
	v_rndne_f32_e32 v90, v88
	v_fmac_f32_e32 v89, 0xb2a5705f, v82
	v_sub_f32_e32 v88, v88, v90
	v_add_f32_e32 v88, v88, v89
	v_exp_f32_e32 v88, v88
	v_cvt_i32_f32_e32 v89, v90
	v_ldexp_f32 v88, v88, v89
	v_mov_b32_e32 v82, v88
	v_add_f32_e32 v88, v117, v91
	v_mul_f32_e32 v89, 0xbfb8aa3b, v88
	v_fma_f32 v90, v88, s20, -v89
	v_rndne_f32_e32 v91, v89
	v_fmac_f32_e32 v90, 0xb2a5705f, v88
	v_sub_f32_e32 v89, v89, v91
	v_add_f32_e32 v89, v89, v90
	v_exp_f32_e32 v89, v89
	v_cvt_i32_f32_e32 v90, v91
	v_ldexp_f32 v89, v89, v90
	v_mov_b32_e32 v88, v89
	v_add_f32_e32 v88, 1.0, v88
	v_div_scale_f32 v89, s[0:1], v88, v88, 1.0
	v_rcp_f32_e32 v90, v89
	s_nop 0
	v_fma_f32 v91, -v89, v90, 1.0
	v_fmac_f32_e32 v90, v91, v90
	v_div_scale_f32 v91, vcc, 1.0, v88, 1.0
	v_mul_f32_e32 v92, v91, v90
	v_fma_f32 v93, -v89, v92, v91
	v_fmac_f32_e32 v92, v93, v90
	v_fma_f32 v89, -v89, v92, v91
	v_div_fmas_f32 v89, v89, v90, v92
	v_div_fixup_f32 v88, v89, v88, 1.0
	v_mul_f32_e32 v89, v118, v84
	v_mul_f32_e32 v90, v89, v89
	s_nop 1
	v_mov_b32_dpp v90, v90 quad_perm:[1,0,3,2] row_mask:0xf bank_mask:0xf bound_ctrl:1
	v_fmac_f32_e32 v90, v89, v89
	s_nop 1
	v_add_f32_dpp v90, v90, v90 quad_perm:[2,3,0,1] row_mask:0xf bank_mask:0xf bound_ctrl:1
	s_nop 1
	v_add_f32_dpp v90, v90, v90 row_half_mirror row_mask:0xf bank_mask:0xf bound_ctrl:1
	s_nop 1
	v_add_f32_dpp v90, v90, v90 row_mirror row_mask:0xf bank_mask:0xf bound_ctrl:1
	s_nop 0
	v_readlane_b32 s1, v90, 16
	v_readlane_b32 s0, v90, 0
	s_nop 0
	v_mov_b32_e32 v91, s1
	v_readlane_b32 s1, v90, 48
	v_add_f32_e32 v91, s0, v91
	v_readlane_b32 s0, v90, 32
	v_mov_b32_e32 v90, s1
	s_nop 0
	v_add_f32_e32 v90, s0, v90
	v_add_f32_e32 v90, v91, v90
	v_cmp_gt_f32_e32 vcc, s7, v90
	v_mul_f32_e32 v91, 0x4f800000, v90
	s_nop 0
	v_cndmask_b32_e32 v90, v90, v91, vcc
	v_sqrt_f32_e32 v91, v90
	s_nop 0
	v_add_u32_e32 v92, -1, v91
	v_fma_f32 v93, -v92, v91, v90
	v_cmp_ge_f32_e64 s[0:1], 0, v93
	v_add_u32_e32 v93, 1, v91
	s_nop 0
	v_cndmask_b32_e64 v92, v91, v92, s[0:1]
	v_fma_f32 v91, -v93, v91, v90
	v_cmp_lt_f32_e64 s[0:1], 0, v91
	s_nop 1
	v_cndmask_b32_e64 v91, v92, v93, s[0:1]
	v_mul_f32_e32 v92, 0x37800000, v91
	v_cndmask_b32_e32 v91, v91, v92, vcc
	v_cmp_class_f32_e32 vcc, v90, v207
	s_nop 1
	v_cndmask_b32_e32 v90, v91, v90, vcc
	v_max_f32_e32 v90, 0x2b8cbccc, v90
	v_div_scale_f32 v91, s[0:1], v90, v90, v89
	v_rcp_f32_e32 v92, v91
	s_nop 0
	v_fma_f32 v93, -v91, v92, 1.0
	v_fmac_f32_e32 v92, v93, v92
	v_div_scale_f32 v93, vcc, v89, v90, v89
	v_mul_f32_e32 v115, v93, v92
	v_fma_f32 v144, -v91, v115, v93
	v_fmac_f32_e32 v115, v144, v92
	v_fma_f32 v91, -v91, v115, v93
	v_div_fmas_f32 v91, v91, v92, v115
	v_div_fixup_f32 v90, v91, v90, v89
	v_add_f32_e32 v89, -1.0, v88
	v_fma_f32 v89, v119, v89, 1.0
	v_mul_f32_e32 v84, v84, v89
	v_mul_f32_e32 v91, v88, v90
	v_mul_f32_e32 v88, v83, v84
	v_mul_f32_e32 v89, v120, v88
	s_nop 1
	v_mov_b32_dpp v89, v89 quad_perm:[1,0,3,2] row_mask:0xf bank_mask:0xf bound_ctrl:1
	v_fmac_f32_e32 v89, v120, v88
	s_nop 1
	v_add_f32_dpp v88, v89, v89 quad_perm:[2,3,0,1] row_mask:0xf bank_mask:0xf bound_ctrl:1
	s_nop 1
	v_add_f32_dpp v88, v88, v88 row_half_mirror row_mask:0xf bank_mask:0xf bound_ctrl:1
	s_nop 1
	v_add_f32_dpp v88, v88, v88 row_mirror row_mask:0xf bank_mask:0xf bound_ctrl:1
	s_nop 0
	v_readlane_b32 s0, v88, 0
	v_readlane_b32 s11, v88, 16
	v_readlane_b32 s1, v88, 32
	v_readlane_b32 s13, v88, 48
	v_mad_i64_i32 v[88:89], s[2:3], s37, v143, v[104:105]
	global_store_dword v[88:89], v90, off nt
	global_store_dword v[88:89], v91, off offset:256 nt
	global_store_dword v[88:89], v82, off offset:512 nt
	global_store_dword v[88:89], v84, off offset:768 nt
	global_store_dword v[88:89], v83, off offset:1024 nt
	global_store_dword v[88:89], v85, off offset:1280 nt
	s_and_saveexec_b64 s[2:3], s[42:43]
	s_cbranch_execz .LBB0_100
	s_add_i32 vcc_lo, s19, s31
	s_ashr_i32 vcc_hi, vcc_lo, 31
	s_lshl_b64 vcc, vcc, 2
	s_add_u32 vcc_lo, s9, vcc_lo
	v_mov_b32_e32 v82, s11
	v_mov_b32_e32 v83, s13
	s_addc_u32 vcc_hi, s15, vcc_hi
	v_pk_add_f32 v[82:83], s[0:1], v[82:83]
	s_nop 0
	v_add_f32_e32 v84, v82, v83
	v_mov_b64_e32 v[82:83], vcc
	global_store_dword v[82:83], v84, off
; #define LAS __attribute__((address_space(3)))
; __device__ __forceinline__ void phase_prep(const Args& A, const Ctx& C0, int l) {
;     ...
;         for (int tt = 0; tt < 8; ++tt) {
;             const float aw = outw[tt * 512 + c], aa = outa[tt * 512 + c];
;             const int row = row0 + tt;
;             const LAS float* cu = raw + (tt + 1) * DSH; const LAS float* pv = raw + tt * DSH;
;             const float r = cu[c] + (pv[c] - cu[c]) * mu_r, k = cu[512 + c] + (pv[512 + c] - cu[512 + c]) * mu_k, v = cu[1024 + c] + (pv[1024 + c] - cu[1024 + c]) * mu_v;
;             const float lw = w0 + aw; const float z = -lw;
;             const float sp = fmaxf(z, 0.f) + logf(1.f + expf(-fabsf(z)));
;             const float wraw = -sp - 0.5f; const float decay = expf(-expf(wraw));
;             const float ai = 1.f / (1.f + expf(-(a0 + aa)));
;             const float kkr = k * kkc; const float ss = wave_sum_l(kkr * kkr, C.lane);
;             const float kk = kkr / fmaxf(sqrtf(ss), 1e-12f);
;             const float k2 = k * (1.f + (ai - 1.f) * kac); const float b = kk * ai;
;             const float rk = wave_sum_l(r * k2 * rkc, C.lane);
;             float* s = SCN + (size_t)row * 3072 + head * 384 + C.lane;
;             __builtin_nontemporal_store(kk, s); __builtin_nontemporal_store(b, s + 64); __builtin_nontemporal_store(decay, s + 128); __builtin_nontemporal_store(k2, s + 192); __builtin_nontemporal_store(r, s + 256); __builtin_nontemporal_store(v, s + 320);
;             if (C.lane == 0) RKB[row * 8 + head] = rk;
.LBB0_100:
	s_or_b64 exec, exec, s[2:3]
	v_add_u32_e32 v82, 0x10300, v87
	ds_read_b32 v90, v82
	v_add_u32_e32 v82, 0x14300, v87
	ds_read_b32 v87, v82
	ds_read2st64_b32 v[82:83], v86 offset0:42 offset1:52
	ds_read2st64_b32 v[88:89], v86 offset0:26 offset1:34
	ds_read2st64_b32 v[84:85], v86 offset0:60 offset1:68
	s_add_i32 s2, s37, 1
	s_waitcnt lgkmcnt(0)
	v_sub_f32_e32 v88, v88, v83
	v_sub_f32_e32 v82, v82, v85
	v_fmac_f32_e32 v85, v123, v82
	v_add_f32_e32 v82, v116, v90
	v_fmac_f32_e32 v83, v121, v88
	v_mul_f32_e64 v88, |v82|, s20
	v_sub_f32_e32 v86, v89, v84
	v_fma_f32 v89, |v82|, s20, -v88
	v_rndne_f32_e32 v90, v88
	v_fma_f32 v89, |v82|, s21, v89
	v_sub_f32_e32 v88, v88, v90
	v_add_f32_e32 v88, v88, v89
	v_exp_f32_e32 v88, v88
	v_cvt_i32_f32_e32 v89, v90
	v_fma_f32 v84, v122, v86, v84
	v_max_f32_e64 v86, -v82, 0
	v_ldexp_f32 v88, v88, v89
	v_mov_b32_e32 v82, v88
	v_add_f32_e32 v82, 1.0, v82
	v_cmp_gt_f32_e32 vcc, s35, v82
	s_nop 1
	v_cndmask_b32_e64 v88, 0, 32, vcc
	v_ldexp_f32 v82, v82, v88
	v_log_f32_e32 v82, v82
	s_nop 0
	v_mul_f32_e32 v88, 0x3f317217, v82
	v_fma_f32 v88, v82, s4, -v88
	v_fmac_f32_e32 v88, 0x3377d1cf, v82
	v_fmac_f32_e32 v88, 0x3f317217, v82
	v_cmp_lt_f32_e64 s[0:1], |v82|, s34
	s_nop 1
	v_cndmask_b32_e64 v82, v82, v88, s[0:1]
	v_cndmask_b32_e32 v88, 0, v142, vcc
	v_sub_f32_e32 v82, v82, v88
	v_add_f32_e32 v82, v86, v82
	v_sub_f32_e32 v82, -0.5, v82
	v_mul_f32_e32 v86, 0x3fb8aa3b, v82
	v_fma_f32 v88, v82, s97, -v86
	v_rndne_f32_e32 v89, v86
	v_fmac_f32_e32 v88, 0x32a5705f, v82
	v_sub_f32_e32 v86, v86, v89
	v_add_f32_e32 v86, v86, v88
	v_exp_f32_e32 v86, v86
	v_cvt_i32_f32_e32 v88, v89
	v_ldexp_f32 v86, v86, v88
	v_mov_b32_e32 v82, v86
	v_mul_f32_e32 v86, 0xbfb8aa3b, v82
	v_fma_f32 v88, v82, s20, -v86
	v_rndne_f32_e32 v89, v86
	v_fmac_f32_e32 v88, 0xb2a5705f, v82
	v_sub_f32_e32 v86, v86, v89
	v_add_f32_e32 v86, v86, v88
	v_exp_f32_e32 v86, v86
	v_cvt_i32_f32_e32 v88, v89
	v_ldexp_f32 v86, v86, v88
	v_mov_b32_e32 v82, v86
	v_add_f32_e32 v86, v117, v87
	v_mul_f32_e32 v87, 0xbfb8aa3b, v86
	v_fma_f32 v88, v86, s20, -v87
	v_rndne_f32_e32 v89, v87
	v_fmac_f32_e32 v88, 0xb2a5705f, v86
	v_sub_f32_e32 v87, v87, v89
	v_add_f32_e32 v87, v87, v88
	v_exp_f32_e32 v87, v87
	v_cvt_i32_f32_e32 v88, v89
	v_ldexp_f32 v87, v87, v88
	v_mov_b32_e32 v86, v87
	v_add_f32_e32 v86, 1.0, v86
	v_div_scale_f32 v87, s[0:1], v86, v86, 1.0
	v_rcp_f32_e32 v88, v87
	s_nop 0
	v_fma_f32 v89, -v87, v88, 1.0
	v_fmac_f32_e32 v88, v89, v88
	v_div_scale_f32 v89, vcc, 1.0, v86, 1.0
	v_mul_f32_e32 v90, v89, v88
	v_fma_f32 v91, -v87, v90, v89
	v_fmac_f32_e32 v90, v91, v88
	v_fma_f32 v87, -v87, v90, v89
	v_div_fmas_f32 v87, v87, v88, v90
	v_div_fixup_f32 v86, v87, v86, 1.0
	v_mul_f32_e32 v87, v118, v84
	v_mul_f32_e32 v88, v87, v87
	s_nop 1
	v_mov_b32_dpp v88, v88 quad_perm:[1,0,3,2] row_mask:0xf bank_mask:0xf bound_ctrl:1
	v_fmac_f32_e32 v88, v87, v87
	s_nop 1
	v_add_f32_dpp v88, v88, v88 quad_perm:[2,3,0,1] row_mask:0xf bank_mask:0xf bound_ctrl:1
	s_nop 1
	v_add_f32_dpp v88, v88, v88 row_half_mirror row_mask:0xf bank_mask:0xf bound_ctrl:1
	s_nop 1
	v_add_f32_dpp v88, v88, v88 row_mirror row_mask:0xf bank_mask:0xf bound_ctrl:1
	s_nop 0
	v_readlane_b32 s1, v88, 16
	v_readlane_b32 s0, v88, 0
	s_nop 0
	v_mov_b32_e32 v89, s1
	v_readlane_b32 s1, v88, 48
	v_add_f32_e32 v89, s0, v89
	v_readlane_b32 s0, v88, 32
	v_mov_b32_e32 v88, s1
	s_nop 0
	v_add_f32_e32 v88, s0, v88
	v_add_f32_e32 v88, v89, v88
	v_cmp_gt_f32_e32 vcc, s7, v88
	v_mul_f32_e32 v89, 0x4f800000, v88
	s_nop 0
	v_cndmask_b32_e32 v88, v88, v89, vcc
	v_sqrt_f32_e32 v89, v88
	s_nop 0
	v_add_u32_e32 v90, -1, v89
	v_fma_f32 v91, -v90, v89, v88
	v_cmp_ge_f32_e64 s[0:1], 0, v91
	v_add_u32_e32 v91, 1, v89
	s_nop 0
	v_cndmask_b32_e64 v90, v89, v90, s[0:1]
	v_fma_f32 v89, -v91, v89, v88
	v_cmp_lt_f32_e64 s[0:1], 0, v89
	s_nop 1
	v_cndmask_b32_e64 v89, v90, v91, s[0:1]
	v_mul_f32_e32 v90, 0x37800000, v89
	v_cndmask_b32_e32 v89, v89, v90, vcc
	v_cmp_class_f32_e32 vcc, v88, v207
	s_nop 1
	v_cndmask_b32_e32 v88, v89, v88, vcc
	v_max_f32_e32 v88, 0x2b8cbccc, v88
	v_div_scale_f32 v89, s[0:1], v88, v88, v87
	v_rcp_f32_e32 v90, v89
	s_nop 0
	v_fma_f32 v91, -v89, v90, 1.0
	v_fmac_f32_e32 v90, v91, v90
	v_div_scale_f32 v91, vcc, v87, v88, v87
	v_mul_f32_e32 v92, v91, v90
	v_fma_f32 v93, -v89, v92, v91
	v_fmac_f32_e32 v92, v93, v90
	v_fma_f32 v89, -v89, v92, v91
	v_div_fmas_f32 v89, v89, v90, v92
	v_div_fixup_f32 v88, v89, v88, v87
	v_add_f32_e32 v87, -1.0, v86
	v_fma_f32 v87, v119, v87, 1.0
	v_mul_f32_e32 v84, v84, v87
	v_mul_f32_e32 v89, v86, v88
	v_mul_f32_e32 v86, v83, v84
	v_mul_f32_e32 v87, v120, v86
	s_nop 1
	v_mov_b32_dpp v87, v87 quad_perm:[1,0,3,2] row_mask:0xf bank_mask:0xf bound_ctrl:1
	v_fmac_f32_e32 v87, v120, v86
	s_nop 1
	v_add_f32_dpp v86, v87, v87 quad_perm:[2,3,0,1] row_mask:0xf bank_mask:0xf bound_ctrl:1
	s_nop 1
	v_add_f32_dpp v86, v86, v86 row_half_mirror row_mask:0xf bank_mask:0xf bound_ctrl:1
	s_nop 1
	v_add_f32_dpp v86, v86, v86 row_mirror row_mask:0xf bank_mask:0xf bound_ctrl:1
	s_nop 0
	v_readlane_b32 s0, v86, 0
	v_readlane_b32 s11, v86, 16
	v_readlane_b32 s1, v86, 32
	v_readlane_b32 s13, v86, 48
	v_mad_i64_i32 v[86:87], s[2:3], s2, v143, v[104:105]
	global_store_dword v[86:87], v88, off nt
	global_store_dword v[86:87], v89, off offset:256 nt
	global_store_dword v[86:87], v82, off offset:512 nt
	global_store_dword v[86:87], v84, off offset:768 nt
	global_store_dword v[86:87], v83, off offset:1024 nt
	global_store_dword v[86:87], v85, off offset:1280 nt
	s_and_saveexec_b64 s[2:3], s[42:43]
	s_cbranch_execz .LBB0_97
	s_add_i32 s75, s19, s31
	s_add_i32 vcc_lo, s75, 8
	s_ashr_i32 vcc_hi, vcc_lo, 31
	s_lshl_b64 vcc, vcc, 2
	s_add_u32 vcc_lo, s9, vcc_lo
	v_mov_b32_e32 v82, s11
	v_mov_b32_e32 v83, s13
	s_addc_u32 vcc_hi, s15, vcc_hi
	v_pk_add_f32 v[82:83], s[0:1], v[82:83]
	s_nop 0
	v_add_f32_e32 v84, v82, v83
	v_mov_b64_e32 v[82:83], vcc
	global_store_dword v[82:83], v84, off
	s_branch .LBB0_97
